# light sixth slot (L1 dn2 + w_s in the layer-1 in-proj partial round), other slots as in the current best
# baseline (speedup 1.0000x reference)
; __device__ __forceinline__ void prologue(const kptr_t kp, LAS float* scr, int gw, int NGW, int lane) {
;     ...
;     for (int it = gw; it < IT_TOTAL; it += NGW) {
;         int r = it;
.Lhop4_skip:
	s_cmp_lt_u32 s2, 44
	s_cbranch_scc1 .Lslot_5_skip
	v_writelane_b32 v250, s3, 0
	v_writelane_b32 v250, s4, 1
	v_writelane_b32 v250, s5, 2
	v_writelane_b32 v250, s6, 3
	v_writelane_b32 v250, s7, 4
	v_writelane_b32 v250, s8, 5
	v_writelane_b32 v250, s9, 6
	v_writelane_b32 v250, s10, 7
	v_writelane_b32 v250, s11, 8
	v_writelane_b32 v250, s12, 9
	v_writelane_b32 v250, s13, 10
	v_writelane_b32 v250, s14, 11
	v_writelane_b32 v250, s15, 12
	v_writelane_b32 v250, s16, 13
	v_writelane_b32 v250, s17, 14
	v_writelane_b32 v250, s18, 15
	v_writelane_b32 v250, s19, 16
	v_writelane_b32 v250, s20, 17
	v_writelane_b32 v250, s21, 18
	v_writelane_b32 v250, s22, 19
	v_writelane_b32 v250, s23, 20
	v_writelane_b32 v250, s24, 21
	v_writelane_b32 v250, s25, 22
	v_writelane_b32 v250, s26, 23
	v_writelane_b32 v250, s27, 24
	v_writelane_b32 v250, s28, 25
	v_writelane_b32 v250, s29, 26
	v_writelane_b32 v250, s30, 27
	v_writelane_b32 v250, s31, 28
	v_writelane_b32 v250, s32, 29
	v_writelane_b32 v250, s33, 30
	v_writelane_b32 v250, s34, 31
	v_writelane_b32 v250, s35, 32
	v_writelane_b32 v250, s36, 33
	v_writelane_b32 v250, s37, 34
	v_writelane_b32 v250, s38, 35
	v_writelane_b32 v250, s39, 36
	v_writelane_b32 v250, s40, 37
	v_writelane_b32 v250, s41, 38
	v_writelane_b32 v250, s42, 39
	v_writelane_b32 v250, s43, 40
	v_writelane_b32 v250, s44, 41
	v_writelane_b32 v250, s45, 42
	v_writelane_b32 v250, s46, 43
	v_writelane_b32 v250, s47, 44
	v_writelane_b32 v250, s48, 45
	v_writelane_b32 v250, s49, 46
	v_writelane_b32 v250, s50, 47
	v_writelane_b32 v250, s51, 48
	v_writelane_b32 v250, s52, 49
	v_writelane_b32 v250, s53, 50
	v_writelane_b32 v250, s54, 51
	v_writelane_b32 v250, s55, 52
	v_writelane_b32 v250, s56, 53
	v_writelane_b32 v250, s57, 54
	v_writelane_b32 v250, s58, 55
	v_writelane_b32 v250, s59, 56
	v_writelane_b32 v250, s60, 57
	v_writelane_b32 v250, s61, 58
	v_writelane_b32 v250, s62, 59
	v_writelane_b32 v250, s63, 60
	v_writelane_b32 v250, s64, 61
	v_writelane_b32 v250, s65, 62
	v_writelane_b32 v250, s66, 63
	v_writelane_b32 v251, s67, 0
	v_writelane_b32 v251, s68, 1
	v_writelane_b32 v251, s69, 2
	v_writelane_b32 v251, s70, 3
	v_writelane_b32 v251, s71, 4
	v_writelane_b32 v251, s72, 5
	v_writelane_b32 v251, s73, 6
	v_writelane_b32 v251, s74, 7
	v_writelane_b32 v251, s75, 8
	v_writelane_b32 v251, s76, 9
	v_writelane_b32 v251, s77, 10
	v_writelane_b32 v251, s78, 11
	v_writelane_b32 v251, s79, 12
	v_writelane_b32 v251, s80, 13
	v_writelane_b32 v251, s81, 14
	v_writelane_b32 v251, s82, 15
	v_writelane_b32 v251, s83, 16
	v_writelane_b32 v251, s84, 17
	v_writelane_b32 v251, s85, 18
	v_writelane_b32 v251, s86, 19
	v_writelane_b32 v251, s87, 20
	v_writelane_b32 v251, s88, 21
	v_writelane_b32 v251, s89, 22
	v_writelane_b32 v251, s90, 23
	v_writelane_b32 v251, s91, 24
	v_writelane_b32 v251, s92, 25
	v_writelane_b32 v251, s93, 26
	v_writelane_b32 v251, s94, 27
	v_writelane_b32 v251, s95, 28
	v_writelane_b32 v251, s96, 29
	v_writelane_b32 v251, s97, 30
	v_mov_b32_e32 v236, v200
	v_mov_b32_e32 v237, v201
	v_mov_b32_e32 v238, v202
	v_mov_b32_e32 v239, v203
	v_mov_b32_e32 v240, v204
	v_mov_b32_e32 v241, v205
	v_mov_b32_e32 v242, v206
	v_mov_b32_e32 v243, v207
	v_mov_b32_e32 v244, v208
	v_mov_b32_e32 v245, v209
	v_mov_b32_e32 v246, v210
	v_mov_b32_e32 v247, v211
	s_mov_b32 s98, 0x5320
	s_mov_b32 s99, 0x6a0
	s_mov_b32 s100, 0x6380
	s_mov_b32 s101, 15
	s_branch .Lcv_hop3

; __device__ __forceinline__ void prologue(const kptr_t kp, LAS float* scr, int gw, int NGW, int lane) {
;     ...
;     for (int it = gw; it < IT_TOTAL; it += NGW) {
;         int r = it;
.LBB0_2098:
	s_cmp_lt_u32 s2, 8
	s_cbranch_scc1 .Lslot_6_skip
	v_writelane_b32 v250, s3, 0
	v_writelane_b32 v250, s4, 1
	v_writelane_b32 v250, s5, 2
	v_writelane_b32 v250, s6, 3
	v_writelane_b32 v250, s7, 4
	v_writelane_b32 v250, s8, 5
	v_writelane_b32 v250, s9, 6
	v_writelane_b32 v250, s10, 7
	v_writelane_b32 v250, s11, 8
	v_writelane_b32 v250, s12, 9
	v_writelane_b32 v250, s13, 10
	v_writelane_b32 v250, s14, 11
	v_writelane_b32 v250, s15, 12
	v_writelane_b32 v250, s16, 13
	v_writelane_b32 v250, s17, 14
	v_writelane_b32 v250, s18, 15
	v_writelane_b32 v250, s19, 16
	v_writelane_b32 v250, s20, 17
	v_writelane_b32 v250, s21, 18
	v_writelane_b32 v250, s22, 19
	v_writelane_b32 v250, s23, 20
	v_writelane_b32 v250, s24, 21
	v_writelane_b32 v250, s25, 22
	v_writelane_b32 v250, s26, 23
	v_writelane_b32 v250, s27, 24
	v_writelane_b32 v250, s28, 25
	v_writelane_b32 v250, s29, 26
	v_writelane_b32 v250, s30, 27
	v_writelane_b32 v250, s31, 28
	v_writelane_b32 v250, s32, 29
	v_writelane_b32 v250, s33, 30
	v_writelane_b32 v250, s34, 31
	v_writelane_b32 v250, s35, 32
	v_writelane_b32 v250, s36, 33
	v_writelane_b32 v250, s37, 34
	v_writelane_b32 v250, s38, 35
	v_writelane_b32 v250, s39, 36
	v_writelane_b32 v250, s40, 37
	v_writelane_b32 v250, s41, 38
	v_writelane_b32 v250, s42, 39
	v_writelane_b32 v250, s43, 40
	v_writelane_b32 v250, s44, 41
	v_writelane_b32 v250, s45, 42
	v_writelane_b32 v250, s46, 43
	v_writelane_b32 v250, s47, 44
	v_writelane_b32 v250, s48, 45
	v_writelane_b32 v250, s49, 46
	v_writelane_b32 v250, s50, 47
	v_writelane_b32 v250, s51, 48
	v_writelane_b32 v250, s52, 49
	v_writelane_b32 v250, s53, 50
	v_writelane_b32 v250, s54, 51
	v_writelane_b32 v250, s55, 52
	v_writelane_b32 v250, s56, 53
	v_writelane_b32 v250, s57, 54
	v_writelane_b32 v250, s58, 55
	v_writelane_b32 v250, s59, 56
	v_writelane_b32 v250, s60, 57
	v_writelane_b32 v250, s61, 58
	v_writelane_b32 v250, s62, 59
	v_writelane_b32 v250, s63, 60
	v_writelane_b32 v250, s64, 61
	v_writelane_b32 v250, s65, 62
	v_writelane_b32 v250, s66, 63
	v_writelane_b32 v251, s67, 0
	v_writelane_b32 v251, s68, 1
	v_writelane_b32 v251, s69, 2
	v_writelane_b32 v251, s70, 3
	v_writelane_b32 v251, s71, 4
	v_writelane_b32 v251, s72, 5
	v_writelane_b32 v251, s73, 6
	v_writelane_b32 v251, s74, 7
	v_writelane_b32 v251, s75, 8
	v_writelane_b32 v251, s76, 9
	v_writelane_b32 v251, s77, 10
	v_writelane_b32 v251, s78, 11
	v_writelane_b32 v251, s79, 12
	v_writelane_b32 v251, s80, 13
	v_writelane_b32 v251, s81, 14
	v_writelane_b32 v251, s82, 15
	v_writelane_b32 v251, s83, 16
	v_writelane_b32 v251, s84, 17
	v_writelane_b32 v251, s85, 18
	v_writelane_b32 v251, s86, 19
	v_writelane_b32 v251, s87, 20
	v_writelane_b32 v251, s88, 21
	v_writelane_b32 v251, s89, 22
	v_writelane_b32 v251, s90, 23
	v_writelane_b32 v251, s91, 24
	v_writelane_b32 v251, s92, 25
	v_writelane_b32 v251, s93, 26
	v_writelane_b32 v251, s94, 27
	v_writelane_b32 v251, s95, 28
	v_writelane_b32 v251, s96, 29
	v_writelane_b32 v251, s97, 30
	v_mov_b32_e32 v236, v200
	v_mov_b32_e32 v237, v201
	v_mov_b32_e32 v238, v202
	v_mov_b32_e32 v239, v203
	v_mov_b32_e32 v240, v204
	v_mov_b32_e32 v241, v205
	v_mov_b32_e32 v242, v206
	v_mov_b32_e32 v243, v207
	v_mov_b32_e32 v244, v208
	v_mov_b32_e32 v245, v209
	v_mov_b32_e32 v246, v210
	v_mov_b32_e32 v247, v211
	s_mov_b32 s98, 0x6340
	s_mov_b32 s99, 0x7c0
	s_mov_b32 s100, 0x7180
	s_mov_b32 s101, 16
	s_branch .Lcv_hop4
